# lru round: next-tile row prefetch issued after the look-back fold so the look-back's waits do not include the row loads
# baseline (speedup 1.0000x reference)
; #define LAS __attribute__((address_space(3)))
; __device__ __forceinline__ float bflo(unsigned w) { return __uint_as_float(w << 16); }
; __device__ __forceinline__ float bfhi(unsigned w) { return __uint_as_float(w & 0xffff0000u); }
; __device__ __forceinline__ u32x4 pack8(f32x4 a, f32x4 b) { u32x4 w; w.x = cvtpk(a[0], a[1]); w.y = cvtpk(a[2], a[3]); w.z = cvtpk(b[0], b[1]); w.w = cvtpk(b[2], b[3]); return w; }
; template <int MODE> __device__ __forceinline__ void lru_phase(const Params& P, LAS unsigned char* lds, int l, int tid_in) {
;     ...
; #pragma unroll
;             for (int j = 0; j < 2; ++j) {
;                 f32x4 a0 = *(const LAS f32x4*)(cwl + 512 + c8 * 8), a1 = *(const LAS f32x4*)(cwl + 512 + c8 * 8 + 4);
; #pragma unroll
;                 for (int i = 0; i < 4; ++i) { const u32x4 xw = xr[j][i]; f32x4 x0, x1; const f32x4 w0 = *(const LAS f32x4*)(cwl + i * 128 + c8 * 8), w1 = *(const LAS f32x4*)(cwl + i * 128 + c8 * 8 + 4);
;                     x0[0] = bflo(xw.x); x0[1] = bfhi(xw.x); x0[2] = bflo(xw.y); x0[3] = bfhi(xw.y); x1[0] = bflo(xw.z); x1[1] = bfhi(xw.z); x1[2] = bflo(xw.w); x1[3] = bfhi(xw.w);
;                     a0 += w0 * x0; a1 += w1 * x1; }
;                 *(LAS u32x4*)(xcb + (r0 + 32 * j) * 136 + c8 * 8) = pack8(a0, a1);
;             }
;             if (tile + tstride < NTILE64) lru_load_rows(P, l, tile + tstride, r0, c0, xr);
.Lh0_none:
	v_lshlrev_b32_e32 v16, 16, v120
	v_and_b32_e32 v17, 0xffff0000, v120
	v_lshlrev_b32_e32 v18, 16, v121
	v_and_b32_e32 v19, 0xffff0000, v121
	v_lshlrev_b32_e32 v20, 16, v122
	v_and_b32_e32 v21, 0xffff0000, v122
	v_lshlrev_b32_e32 v22, 16, v123
	v_and_b32_e32 v23, 0xffff0000, v123
	s_waitcnt lgkmcnt(2)
	v_pk_fma_f32 v[8:9], v[8:9], v[16:17], v[0:1]
	v_pk_fma_f32 v[10:11], v[10:11], v[18:19], v[2:3]
	v_pk_fma_f32 v[12:13], v[12:13], v[20:21], v[4:5]
	v_pk_fma_f32 v[14:15], v[14:15], v[22:23], v[6:7]
	ds_read_b128 v[0:3], v183 offset:1024
	ds_read_b128 v[4:7], v183 offset:1040
	v_lshlrev_b32_e32 v16, 16, v124
	v_and_b32_e32 v17, 0xffff0000, v124
	v_lshlrev_b32_e32 v18, 16, v125
	v_and_b32_e32 v19, 0xffff0000, v125
	v_lshlrev_b32_e32 v20, 16, v126
	v_and_b32_e32 v21, 0xffff0000, v126
	v_lshlrev_b32_e32 v22, 16, v127
	v_and_b32_e32 v23, 0xffff0000, v127
	s_waitcnt lgkmcnt(2)
	v_pk_fma_f32 v[10:11], v[26:27], v[18:19], v[10:11]
	v_pk_fma_f32 v[8:9], v[24:25], v[16:17], v[8:9]
	v_pk_fma_f32 v[14:15], v[30:31], v[22:23], v[14:15]
	v_pk_fma_f32 v[12:13], v[28:29], v[20:21], v[12:13]
	ds_read_b128 v[24:27], v183 offset:1536
	ds_read_b128 v[28:31], v183 offset:1552
	v_lshlrev_b32_e32 v16, 16, v128
	v_and_b32_e32 v17, 0xffff0000, v128
	v_lshlrev_b32_e32 v18, 16, v129
	v_and_b32_e32 v19, 0xffff0000, v129
	v_lshlrev_b32_e32 v20, 16, v130
	v_and_b32_e32 v21, 0xffff0000, v130
	v_lshlrev_b32_e32 v22, 16, v131
	v_and_b32_e32 v23, 0xffff0000, v131
	s_waitcnt lgkmcnt(2)
	v_pk_fma_f32 v[8:9], v[0:1], v[16:17], v[8:9]
	v_pk_fma_f32 v[10:11], v[2:3], v[18:19], v[10:11]
	v_pk_fma_f32 v[12:13], v[4:5], v[20:21], v[12:13]
	v_pk_fma_f32 v[14:15], v[6:7], v[22:23], v[14:15]
	v_lshlrev_b32_e32 v16, 16, v132
	v_and_b32_e32 v17, 0xffff0000, v132
	v_lshlrev_b32_e32 v18, 16, v133
	v_and_b32_e32 v19, 0xffff0000, v133
	v_lshlrev_b32_e32 v20, 16, v134
	v_and_b32_e32 v21, 0xffff0000, v134
	v_lshlrev_b32_e32 v22, 16, v135
	v_and_b32_e32 v23, 0xffff0000, v135
	s_waitcnt lgkmcnt(0)
	v_pk_fma_f32 v[2:3], v[26:27], v[18:19], v[10:11]
	v_pk_fma_f32 v[0:1], v[24:25], v[16:17], v[8:9]
	v_pk_fma_f32 v[6:7], v[30:31], v[22:23], v[14:15]
	v_pk_fma_f32 v[4:5], v[28:29], v[20:21], v[12:13]
	v_cvt_pk_bf16_f32 v0, v0, v1
	v_cvt_pk_bf16_f32 v1, v2, v3
	v_cvt_pk_bf16_f32 v2, v4, v5
	v_cvt_pk_bf16_f32 v3, v6, v7
	ds_write_b128 v238, v[0:3]
	ds_read_b128 v[0:3], v182
	ds_read_b128 v[4:7], v182 offset:16
	ds_read_b128 v[8:11], v183
	ds_read_b128 v[12:15], v183 offset:16
	ds_read_b128 v[24:27], v183 offset:512
	ds_read_b128 v[28:31], v183 offset:528
	v_lshlrev_b32_e32 v16, 16, v136
	v_and_b32_e32 v17, 0xffff0000, v136
	v_lshlrev_b32_e32 v18, 16, v137
	v_and_b32_e32 v19, 0xffff0000, v137
	v_lshlrev_b32_e32 v20, 16, v138
	v_and_b32_e32 v21, 0xffff0000, v138
	v_lshlrev_b32_e32 v22, 16, v139
	v_and_b32_e32 v23, 0xffff0000, v139
	s_waitcnt lgkmcnt(2)
	v_pk_fma_f32 v[8:9], v[8:9], v[16:17], v[0:1]
	v_pk_fma_f32 v[10:11], v[10:11], v[18:19], v[2:3]
	v_pk_fma_f32 v[12:13], v[12:13], v[20:21], v[4:5]
	v_pk_fma_f32 v[14:15], v[14:15], v[22:23], v[6:7]
	ds_read_b128 v[0:3], v183 offset:1024
	ds_read_b128 v[4:7], v183 offset:1040
	v_lshlrev_b32_e32 v16, 16, v140
	v_and_b32_e32 v17, 0xffff0000, v140
	v_lshlrev_b32_e32 v18, 16, v141
	v_and_b32_e32 v19, 0xffff0000, v141
	v_lshlrev_b32_e32 v20, 16, v142
	v_and_b32_e32 v21, 0xffff0000, v142
	v_lshlrev_b32_e32 v22, 16, v143
	v_and_b32_e32 v23, 0xffff0000, v143
	s_waitcnt lgkmcnt(2)
	v_pk_fma_f32 v[10:11], v[26:27], v[18:19], v[10:11]
	v_pk_fma_f32 v[8:9], v[24:25], v[16:17], v[8:9]
	v_pk_fma_f32 v[14:15], v[30:31], v[22:23], v[14:15]
	v_pk_fma_f32 v[12:13], v[28:29], v[20:21], v[12:13]
	ds_read_b128 v[24:27], v183 offset:1536
	ds_read_b128 v[28:31], v183 offset:1552
	v_lshlrev_b32_e32 v16, 16, v144
	v_and_b32_e32 v17, 0xffff0000, v144
	v_lshlrev_b32_e32 v18, 16, v145
	v_and_b32_e32 v19, 0xffff0000, v145
	v_lshlrev_b32_e32 v20, 16, v146
	v_and_b32_e32 v21, 0xffff0000, v146
	v_lshlrev_b32_e32 v22, 16, v147
	v_and_b32_e32 v23, 0xffff0000, v147
	s_waitcnt lgkmcnt(2)
	v_pk_fma_f32 v[8:9], v[0:1], v[16:17], v[8:9]
	v_pk_fma_f32 v[10:11], v[2:3], v[18:19], v[10:11]
	v_pk_fma_f32 v[12:13], v[4:5], v[20:21], v[12:13]
	v_pk_fma_f32 v[14:15], v[6:7], v[22:23], v[14:15]
	v_lshlrev_b32_e32 v16, 16, v148
	v_and_b32_e32 v17, 0xffff0000, v148
	v_lshlrev_b32_e32 v18, 16, v149
	v_and_b32_e32 v19, 0xffff0000, v149
	v_lshlrev_b32_e32 v20, 16, v150
	v_and_b32_e32 v21, 0xffff0000, v150
	v_lshlrev_b32_e32 v22, 16, v151
	v_and_b32_e32 v23, 0xffff0000, v151
	s_waitcnt lgkmcnt(0)
	v_pk_fma_f32 v[2:3], v[26:27], v[18:19], v[10:11]
	v_pk_fma_f32 v[0:1], v[24:25], v[16:17], v[8:9]
	v_pk_fma_f32 v[6:7], v[30:31], v[22:23], v[14:15]
	v_pk_fma_f32 v[4:5], v[28:29], v[20:21], v[12:13]
	v_cvt_pk_bf16_f32 v0, v0, v1
	v_cvt_pk_bf16_f32 v1, v2, v3
	v_cvt_pk_bf16_f32 v2, v4, v5
	v_cvt_pk_bf16_f32 v3, v6, v7
	v_readlane_b32 s0, v255, 32
	s_nop 0
	s_add_i32 s0, s42, s0
	s_cmpk_gt_u32 s0, 0x109
	ds_write_b128 v238, v[0:3] offset:8704
; template <int MODE> __device__ __forceinline__ void lru_phase(const Params& P, LAS unsigned char* lds, int l, int tid_in) {
;     ...
;         if (prev >= 0) {
;             float fA = 1.f, fB = 0.f;
;             if (!psamp && (pt0 % LP) != 0) {
;                 const int j0 = (((pt0 - 1) / LP) * LP) / 64, n = prev - j0, per = (n + 3) >> 2, ja = j0 + q * per;
;                 float aa[9], bb[9];
;                 for (unsigned spin = 0; spin < (1u << 20); ++spin) {
;                     bool bad = false;
; #pragma unroll
;                     for (int i = 0; i < 9; ++i) { const bool ok = i < per && ja + i < prev; const int j = ok ? ja + i : j0;
;                         aa[i] = __hip_atomic_load(AGG + (size_t)j * 2048 + cgs, __ATOMIC_RELAXED, __HIP_MEMORY_SCOPE_AGENT); bb[i] = __hip_atomic_load(AGG + (size_t)j * 2048 + 1024 + cgs, __ATOMIC_RELAXED, __HIP_MEMORY_SCOPE_AGENT); }
.LBB0_1159:
	s_lshl_b32 s44, s12, 6
	s_cmpk_gt_i32 s12, 0x101
	s_cselect_b64 s[82:83], -1, 0
	s_cmpk_lt_i32 s12, 0x102
	v_cndmask_b32_e64 v0, 0, 1, s[54:55]
	s_cselect_b64 s[8:9], -1, 0
	v_cmp_ne_u32_e64 s[50:51], 1, v0
	s_andn2_b64 vcc, exec, s[54:55]
	s_cbranch_vccnz .LBB0_1184
	s_mul_hi_u32 s0, s44, 0xfe03f81
	s_lshr_b32 s0, s0, 7
	s_mulk_i32 s0, 0x810
	s_sub_i32 s0, s44, s0
	s_cmp_eq_u32 s0, 0
	s_cselect_b64 s[0:1], -1, 0
	s_or_b64 s[0:1], s[82:83], s[0:1]
	s_and_b64 vcc, exec, s[0:1]
	s_cbranch_vccnz .LBB0_1181
	s_add_i32 s0, s44, -1
	s_sext_i32_i16 s0, s0
	s_mulk_i32 s0, 0x3f81
	s_lshr_b32 s1, s0, 31
	s_ashr_i32 s0, s0, 25
	s_add_i32 s0, s0, s1
	s_mulk_i32 s0, 0x810
	s_sext_i32_i16 s1, s0
	s_bfe_u32 s1, s1, 0x60019
	s_add_i32 s0, s0, s1
	s_sext_i32_i16 s0, s0
	s_ashr_i32 s13, s0, 6
	s_sub_i32 s0, s12, s13
	s_add_i32 s0, s0, 3
	s_ashr_i32 s14, s0, 2
	v_mul_lo_u32 v0, s14, v181
	v_add_u32_e32 v80, s13, v0
	s_cmp_gt_i32 s14, 0
	s_cselect_b64 s[0:1], -1, 0
	v_cmp_gt_i32_e32 vcc, s12, v80
	s_and_b64 vcc, s[0:1], vcc
	s_cmp_gt_i32 s14, 1
	v_add_u32_e32 v4, 1, v80
	s_cselect_b64 s[0:1], -1, 0
	v_cmp_gt_i32_e64 s[52:53], s12, v4
	s_and_b64 s[52:53], s[0:1], s[52:53]
	s_cmp_gt_i32 s14, 2
	v_add_u32_e32 v8, 2, v80
	s_cselect_b64 s[0:1], -1, 0
	v_cmp_gt_i32_e64 s[54:55], s12, v8
	s_and_b64 s[54:55], s[0:1], s[54:55]
	s_cmp_gt_i32 s14, 3
	v_add_u32_e32 v12, 3, v80
	s_cselect_b64 s[0:1], -1, 0
	v_cmp_gt_i32_e64 s[56:57], s12, v12
	s_and_b64 s[56:57], s[0:1], s[56:57]
	s_cmp_gt_i32 s14, 4
	v_add_u32_e32 v16, 4, v80
	s_cselect_b64 s[0:1], -1, 0
	v_cmp_gt_i32_e64 s[58:59], s12, v16
	s_and_b64 s[58:59], s[0:1], s[58:59]
	s_cmp_gt_i32 s14, 5
	v_add_u32_e32 v20, 5, v80
	s_cselect_b64 s[0:1], -1, 0
	v_cmp_gt_i32_e64 s[60:61], s12, v20
	s_and_b64 s[60:61], s[0:1], s[60:61]
	s_cmp_gt_i32 s14, 6
	v_add_u32_e32 v24, 6, v80
	s_cselect_b64 s[0:1], -1, 0
	v_cmp_gt_i32_e64 s[62:63], s12, v24
	s_and_b64 s[62:63], s[0:1], s[62:63]
	s_cmp_gt_i32 s14, 7
	v_add_u32_e32 v28, 7, v80
	s_cselect_b64 s[0:1], -1, 0
	v_cmp_gt_i32_e64 s[64:65], s12, v28
	v_mov_b32_e32 v84, s13
	s_and_b64 s[64:65], s[0:1], s[64:65]
	v_cndmask_b32_e32 v0, v84, v80, vcc
	s_cmp_gt_i32 s14, 8
	v_add_u32_e32 v80, 8, v80
	s_cselect_b64 s[0:1], -1, 0
	v_cmp_gt_i32_e64 s[66:67], s12, v80
	s_and_b64 s[66:67], s[0:1], s[66:67]
	v_cndmask_b32_e64 v4, v84, v4, s[52:53]
	v_cndmask_b32_e64 v8, v84, v8, s[54:55]
	v_cndmask_b32_e64 v12, v84, v12, s[56:57]
	v_cndmask_b32_e64 v16, v84, v16, s[58:59]
	v_cndmask_b32_e64 v20, v84, v20, s[60:61]
	v_cndmask_b32_e64 v24, v84, v24, s[62:63]
	v_cndmask_b32_e64 v28, v84, v28, s[64:65]
	v_cndmask_b32_e64 v84, v84, v80, s[66:67]
	v_ashrrev_i32_e32 v1, 31, v0
	v_ashrrev_i32_e32 v5, 31, v4
	v_ashrrev_i32_e32 v9, 31, v8
	v_ashrrev_i32_e32 v13, 31, v12
	v_ashrrev_i32_e32 v17, 31, v16
	v_ashrrev_i32_e32 v21, 31, v20
	v_ashrrev_i32_e32 v25, 31, v24
	v_ashrrev_i32_e32 v29, 31, v28
	v_ashrrev_i32_e32 v85, 31, v84
	v_lshlrev_b64 v[0:1], 13, v[0:1]
	v_lshlrev_b64 v[4:5], 13, v[4:5]
	v_lshlrev_b64 v[8:9], 13, v[8:9]
	v_lshlrev_b64 v[12:13], 13, v[12:13]
	v_lshlrev_b64 v[16:17], 13, v[16:17]
	v_lshlrev_b64 v[20:21], 13, v[20:21]
	v_lshlrev_b64 v[24:25], 13, v[24:25]
	v_lshlrev_b64 v[28:29], 13, v[28:29]
	v_lshlrev_b64 v[84:85], 13, v[84:85]
	v_lshl_add_u64 v[0:1], s[2:3], 0, v[0:1]
	v_lshlrev_b64 v[82:83], 2, v[158:159]
	v_lshl_add_u64 v[4:5], s[2:3], 0, v[4:5]
	v_lshl_add_u64 v[8:9], s[2:3], 0, v[8:9]
	v_lshl_add_u64 v[12:13], s[2:3], 0, v[12:13]
	v_lshl_add_u64 v[16:17], s[2:3], 0, v[16:17]
	v_lshl_add_u64 v[20:21], s[2:3], 0, v[20:21]
	v_lshl_add_u64 v[24:25], s[2:3], 0, v[24:25]
	v_lshl_add_u64 v[28:29], s[2:3], 0, v[28:29]
	v_lshl_add_u64 v[84:85], s[2:3], 0, v[84:85]
	v_lshl_add_u64 v[0:1], v[0:1], 0, v[82:83]
	s_mov_b64 s[16:17], 0x1000
	v_lshl_add_u64 v[4:5], v[4:5], 0, v[82:83]
	v_lshl_add_u64 v[8:9], v[8:9], 0, v[82:83]
	v_lshl_add_u64 v[12:13], v[12:13], 0, v[82:83]
	v_lshl_add_u64 v[16:17], v[16:17], 0, v[82:83]
	v_lshl_add_u64 v[20:21], v[20:21], 0, v[82:83]
	v_lshl_add_u64 v[24:25], v[24:25], 0, v[82:83]
	v_lshl_add_u64 v[28:29], v[28:29], 0, v[82:83]
	v_lshl_add_u64 v[82:83], v[84:85], 0, v[82:83]
	s_mov_b64 s[22:23], s[28:29]
	s_mov_b64 s[28:29], s[30:31]
	s_mov_b64 s[30:31], s[26:27]
	s_mov_b64 s[26:27], s[36:37]
	s_mov_b64 s[38:39], s[86:87]
	s_mov_b64 s[36:37], s[96:97]
	v_lshl_add_u64 v[2:3], v[0:1], 0, s[16:17]
	v_lshl_add_u64 v[6:7], v[4:5], 0, s[16:17]
	v_lshl_add_u64 v[10:11], v[8:9], 0, s[16:17]
	v_lshl_add_u64 v[14:15], v[12:13], 0, s[16:17]
	v_lshl_add_u64 v[18:19], v[16:17], 0, s[16:17]
	v_lshl_add_u64 v[22:23], v[20:21], 0, s[16:17]
	v_lshl_add_u64 v[26:27], v[24:25], 0, s[16:17]
	v_lshl_add_u64 v[30:31], v[28:29], 0, s[16:17]
	v_lshl_add_u64 v[84:85], v[82:83], 0, s[16:17]
	s_mov_b32 s45, 0x100000
	s_mov_b64 s[86:87], 0
	s_branch .LBB0_1163

; __device__ __forceinline__ u32x4 pack8(f32x4 a, f32x4 b) { u32x4 w; w.x = cvtpk(a[0], a[1]); w.y = cvtpk(a[2], a[3]); w.z = cvtpk(b[0], b[1]); w.w = cvtpk(b[2], b[3]); return w; }
; __device__ __forceinline__ void lru_load_rows(const Params& P, int l, int tile, int r0, int c0, u32x4 (&xr)[2][4]) {
;     const bf16* XR = (const bf16*)(P.ws + WS_XR);
;     const bool samp = tile * 64 >= NPT;
; #pragma unroll
;     for (int j = 0; j < 2; ++j) {
;         const int m = tile * 64 + r0 + 32 * j;
;         const int pos = samp ? ((m - NPT) & 3) : (m % LP);
; #pragma unroll
;         for (int i = 0; i < 4; ++i) {
;             u32x4 v = {0u, 0u, 0u, 0u};
;             if (pos - i >= 0) v = *(const u32x4*)(XR + (size_t)(m - i) * 1024 + c0);
;             else if (samp) { const float* buf = P.in[I_SC] + ((size_t)((l * 128 + ((m - NPT) >> 2)) * 3) + (3 + pos - i)) * 1024 + c0; v = pack8(*(const f32x4*)buf, *(const f32x4*)(buf + 4)); }
;             xr[j][i] = v;
;         }
;     }
; template <int MODE> __device__ __forceinline__ void lru_phase(const Params& P, LAS unsigned char* lds, int l, int tid_in) {
;     ...
;             if (tile + tstride < NTILE64) lru_load_rows(P, l, tile + tstride, r0, c0, xr);
.LBB0_1184:
	s_and_b64 vcc, exec, s[48:49]
	s_cbranch_vccnz .Lpf_moved_done
	v_readlane_b32 s0, v255, 32
	s_nop 1
	s_add_i32 s0, s42, s0
	s_cmpk_gt_u32 s0, 0x109
	s_cbranch_scc1 .LBB0_1158
	s_mov_b64 s[88:89], 0
	s_mov_b64 s[90:91], 0
	s_mov_b64 s[92:93], 0
	s_mov_b64 s[60:61], 0
	s_mov_b64 s[62:63], 0
	s_mov_b64 s[66:67], 0
	v_lshl_add_u32 v0, s0, 6, v177
	v_mul_hi_i32 v1, v0, s71
	v_lshrrev_b32_e32 v2, 31, v1
	v_ashrrev_i32_e32 v1, 7, v1
	v_add_u32_e32 v1, v1, v2
	s_cmpk_gt_u32 s0, 0x101
	v_mul_lo_u32 v1, v1, s73
	v_sub_u32_e32 v1, v0, v1
	s_cselect_b64 s[52:53], -1, 0
	v_cndmask_b32_e64 v4, v1, v154, s[52:53]
	v_cmp_lt_i32_e32 vcc, -1, v4
	v_ashrrev_i32_e32 v1, 31, v0
	s_and_saveexec_b64 s[0:1], vcc
	s_xor_b64 s[0:1], exec, s[0:1]
	s_cbranch_execz .LBB0_1110
	v_lshlrev_b64 v[2:3], 11, v[0:1]
	v_lshl_add_u64 v[2:3], v[168:169], 0, v[2:3]
	global_load_dwordx4 v[120:123], v[2:3], off
.LBB0_1110:
	s_or_saveexec_b64 s[0:1], s[0:1]
	v_add_u32_e32 v2, 0xffffbf80, v0
	v_ashrrev_i32_e32 v2, 2, v2
	v_add_u32_e32 v2, s40, v2
	v_lshl_add_u32 v2, v2, 1, v2
	v_cndmask_b32_e64 v5, 0, 1, s[52:53]
	v_ashrrev_i32_e32 v3, 31, v2
	v_cmp_ne_u32_e64 s[56:57], 1, v5
	s_xor_b64 exec, exec, s[0:1]
	s_cbranch_execz .LBB0_1115
	s_and_b64 vcc, exec, s[56:57]
	s_cbranch_vccnz .LBB0_1114
	v_add_u32_e32 v6, 3, v4
	v_ashrrev_i32_e32 v7, 31, v6
	v_lshl_add_u64 v[6:7], v[2:3], 0, v[6:7]
	v_lshlrev_b64 v[6:7], 12, v[6:7]
	v_lshl_add_u64 v[10:11], v[166:167], 0, v[6:7]
	global_load_dwordx4 v[6:9], v[10:11], off
	s_nop 0
	global_load_dwordx4 v[10:13], v[10:11], off offset:16
	s_waitcnt vmcnt(1)
	v_cvt_pk_bf16_f32 v120, v6, v7
	v_cvt_pk_bf16_f32 v121, v8, v9
	s_waitcnt vmcnt(0)
	v_cvt_pk_bf16_f32 v122, v10, v11
	v_cvt_pk_bf16_f32 v123, v12, v13
	s_branch .LBB0_1115

; __device__ __forceinline__ u32x4 pack8(f32x4 a, f32x4 b) { u32x4 w; w.x = cvtpk(a[0], a[1]); w.y = cvtpk(a[2], a[3]); w.z = cvtpk(b[0], b[1]); w.w = cvtpk(b[2], b[3]); return w; }
; __device__ __forceinline__ void lru_load_rows(const Params& P, int l, int tile, int r0, int c0, u32x4 (&xr)[2][4]) {
;     const bf16* XR = (const bf16*)(P.ws + WS_XR);
;     const bool samp = tile * 64 >= NPT;
; #pragma unroll
;     for (int j = 0; j < 2; ++j) {
;         const int m = tile * 64 + r0 + 32 * j;
;         const int pos = samp ? ((m - NPT) & 3) : (m % LP);
; #pragma unroll
;         for (int i = 0; i < 4; ++i) {
;             u32x4 v = {0u, 0u, 0u, 0u};
;             if (pos - i >= 0) v = *(const u32x4*)(XR + (size_t)(m - i) * 1024 + c0);
;             else if (samp) { const float* buf = P.in[I_SC] + ((size_t)((l * 128 + ((m - NPT) >> 2)) * 3) + (3 + pos - i)) * 1024 + c0; v = pack8(*(const f32x4*)buf, *(const f32x4*)(buf + 4)); }
;             xr[j][i] = v;
;         }
;     }
.LBB0_1117:
	s_andn2_saveexec_b64 s[0:1], s[0:1]
	s_cbranch_execz .LBB0_1121
	s_and_b64 vcc, exec, s[56:57]
	s_cbranch_vccnz .LBB0_1120
	s_mov_b64 s[88:89], exec
	v_lshl_add_u64 v[6:7], v[2:3], 0, v[160:161]
	v_lshlrev_b64 v[6:7], 12, v[6:7]
	v_lshl_add_u64 v[10:11], v[166:167], 0, v[6:7]
	global_load_dwordx4 v[20:23], v[10:11], off
	global_load_dwordx4 v[24:27], v[10:11], off offset:16
	s_branch .LBB0_1121

; __device__ __forceinline__ u32x4 pack8(f32x4 a, f32x4 b) { u32x4 w; w.x = cvtpk(a[0], a[1]); w.y = cvtpk(a[2], a[3]); w.z = cvtpk(b[0], b[1]); w.w = cvtpk(b[2], b[3]); return w; }
; __device__ __forceinline__ void lru_load_rows(const Params& P, int l, int tile, int r0, int c0, u32x4 (&xr)[2][4]) {
;     const bf16* XR = (const bf16*)(P.ws + WS_XR);
;     const bool samp = tile * 64 >= NPT;
; #pragma unroll
;     for (int j = 0; j < 2; ++j) {
;         const int m = tile * 64 + r0 + 32 * j;
;         const int pos = samp ? ((m - NPT) & 3) : (m % LP);
; #pragma unroll
;         for (int i = 0; i < 4; ++i) {
;             u32x4 v = {0u, 0u, 0u, 0u};
;             if (pos - i >= 0) v = *(const u32x4*)(XR + (size_t)(m - i) * 1024 + c0);
;             else if (samp) { const float* buf = P.in[I_SC] + ((size_t)((l * 128 + ((m - NPT) >> 2)) * 3) + (3 + pos - i)) * 1024 + c0; v = pack8(*(const f32x4*)buf, *(const f32x4*)(buf + 4)); }
;             xr[j][i] = v;
;         }
;     }
.LBB0_1123:
	s_andn2_saveexec_b64 s[0:1], s[0:1]
	s_cbranch_execz .LBB0_1127
	s_and_b64 vcc, exec, s[56:57]
	s_cbranch_vccnz .LBB0_1126
	s_mov_b64 s[90:91], exec
	v_lshl_add_u64 v[6:7], v[2:3], 0, v[162:163]
	v_lshlrev_b64 v[6:7], 12, v[6:7]
	v_lshl_add_u64 v[10:11], v[166:167], 0, v[6:7]
	global_load_dwordx4 v[28:31], v[10:11], off
	global_load_dwordx4 v[82:85], v[10:11], off offset:16
	s_branch .LBB0_1127

; __device__ __forceinline__ u32x4 pack8(f32x4 a, f32x4 b) { u32x4 w; w.x = cvtpk(a[0], a[1]); w.y = cvtpk(a[2], a[3]); w.z = cvtpk(b[0], b[1]); w.w = cvtpk(b[2], b[3]); return w; }
; __device__ __forceinline__ void lru_load_rows(const Params& P, int l, int tile, int r0, int c0, u32x4 (&xr)[2][4]) {
;     const bf16* XR = (const bf16*)(P.ws + WS_XR);
;     const bool samp = tile * 64 >= NPT;
; #pragma unroll
;     for (int j = 0; j < 2; ++j) {
;         const int m = tile * 64 + r0 + 32 * j;
;         const int pos = samp ? ((m - NPT) & 3) : (m % LP);
; #pragma unroll
;         for (int i = 0; i < 4; ++i) {
;             u32x4 v = {0u, 0u, 0u, 0u};
;             if (pos - i >= 0) v = *(const u32x4*)(XR + (size_t)(m - i) * 1024 + c0);
;             else if (samp) { const float* buf = P.in[I_SC] + ((size_t)((l * 128 + ((m - NPT) >> 2)) * 3) + (3 + pos - i)) * 1024 + c0; v = pack8(*(const f32x4*)buf, *(const f32x4*)(buf + 4)); }
;             xr[j][i] = v;
;         }
;     }
.LBB0_1129:
	s_andn2_saveexec_b64 s[0:1], s[0:1]
	s_cbranch_execz .LBB0_1133
	s_and_b64 vcc, exec, s[56:57]
	s_cbranch_vccnz .LBB0_1132
	s_mov_b64 s[92:93], exec
	v_lshl_add_u64 v[2:3], v[2:3], 0, v[154:155]
	v_lshlrev_b64 v[2:3], 12, v[2:3]
	v_lshl_add_u64 v[6:7], v[166:167], 0, v[2:3]
	global_load_dwordx4 v[186:189], v[6:7], off
	global_load_dwordx4 v[226:229], v[6:7], off offset:16
	s_branch .LBB0_1133

; __device__ __forceinline__ u32x4 pack8(f32x4 a, f32x4 b) { u32x4 w; w.x = cvtpk(a[0], a[1]); w.y = cvtpk(a[2], a[3]); w.z = cvtpk(b[0], b[1]); w.w = cvtpk(b[2], b[3]); return w; }
; __device__ __forceinline__ void lru_load_rows(const Params& P, int l, int tile, int r0, int c0, u32x4 (&xr)[2][4]) {
;     const bf16* XR = (const bf16*)(P.ws + WS_XR);
;     const bool samp = tile * 64 >= NPT;
; #pragma unroll
;     for (int j = 0; j < 2; ++j) {
;         const int m = tile * 64 + r0 + 32 * j;
;         const int pos = samp ? ((m - NPT) & 3) : (m % LP);
; #pragma unroll
;         for (int i = 0; i < 4; ++i) {
;             u32x4 v = {0u, 0u, 0u, 0u};
;             if (pos - i >= 0) v = *(const u32x4*)(XR + (size_t)(m - i) * 1024 + c0);
;             else if (samp) { const float* buf = P.in[I_SC] + ((size_t)((l * 128 + ((m - NPT) >> 2)) * 3) + (3 + pos - i)) * 1024 + c0; v = pack8(*(const f32x4*)buf, *(const f32x4*)(buf + 4)); }
;             xr[j][i] = v;
;         }
;     }
.LBB0_1135:
	s_or_saveexec_b64 s[0:1], s[0:1]
	v_add_u32_e32 v2, 0xffffbfa0, v0
	v_ashrrev_i32_e32 v2, 2, v2
	v_add_u32_e32 v2, s40, v2
	v_lshl_add_u32 v2, v2, 1, v2
	v_ashrrev_i32_e32 v3, 31, v2
	s_xor_b64 exec, exec, s[0:1]
	s_cbranch_execz .LBB0_1139
	s_and_b64 vcc, exec, s[56:57]
	s_cbranch_vccnz .LBB0_1138
	v_add_u32_e32 v6, 3, v4
	v_ashrrev_i32_e32 v7, 31, v6
	v_lshl_add_u64 v[6:7], v[6:7], 0, v[2:3]
	v_lshlrev_b64 v[6:7], 12, v[6:7]
	v_lshl_add_u64 v[10:11], v[166:167], 0, v[6:7]
	global_load_dwordx4 v[6:9], v[10:11], off
	s_nop 0
	global_load_dwordx4 v[10:13], v[10:11], off offset:16
	s_waitcnt vmcnt(1)
	v_cvt_pk_bf16_f32 v136, v6, v7
	v_cvt_pk_bf16_f32 v137, v8, v9
	s_waitcnt vmcnt(0)
	v_cvt_pk_bf16_f32 v138, v10, v11
	v_cvt_pk_bf16_f32 v139, v12, v13
	s_branch .LBB0_1139

; __device__ __forceinline__ u32x4 pack8(f32x4 a, f32x4 b) { u32x4 w; w.x = cvtpk(a[0], a[1]); w.y = cvtpk(a[2], a[3]); w.z = cvtpk(b[0], b[1]); w.w = cvtpk(b[2], b[3]); return w; }
; __device__ __forceinline__ void lru_load_rows(const Params& P, int l, int tile, int r0, int c0, u32x4 (&xr)[2][4]) {
;     const bf16* XR = (const bf16*)(P.ws + WS_XR);
;     const bool samp = tile * 64 >= NPT;
; #pragma unroll
;     for (int j = 0; j < 2; ++j) {
;         const int m = tile * 64 + r0 + 32 * j;
;         const int pos = samp ? ((m - NPT) & 3) : (m % LP);
; #pragma unroll
;         for (int i = 0; i < 4; ++i) {
;             u32x4 v = {0u, 0u, 0u, 0u};
;             if (pos - i >= 0) v = *(const u32x4*)(XR + (size_t)(m - i) * 1024 + c0);
;             else if (samp) { const float* buf = P.in[I_SC] + ((size_t)((l * 128 + ((m - NPT) >> 2)) * 3) + (3 + pos - i)) * 1024 + c0; v = pack8(*(const f32x4*)buf, *(const f32x4*)(buf + 4)); }
;             xr[j][i] = v;
;         }
;     }
.LBB0_1141:
	s_andn2_saveexec_b64 s[0:1], s[0:1]
	s_cbranch_execz .LBB0_1145
	s_and_b64 vcc, exec, s[56:57]
	s_cbranch_vccnz .LBB0_1144
	s_mov_b64 s[60:61], exec
	v_lshl_add_u64 v[6:7], v[2:3], 0, v[160:161]
	v_lshlrev_b64 v[6:7], 12, v[6:7]
	v_lshl_add_u64 v[10:11], v[166:167], 0, v[6:7]
	global_load_dwordx4 v[20:23], v[10:11], off
	global_load_dwordx4 v[24:27], v[10:11], off offset:16
	s_branch .LBB0_1145

; __device__ __forceinline__ u32x4 pack8(f32x4 a, f32x4 b) { u32x4 w; w.x = cvtpk(a[0], a[1]); w.y = cvtpk(a[2], a[3]); w.z = cvtpk(b[0], b[1]); w.w = cvtpk(b[2], b[3]); return w; }
; __device__ __forceinline__ void lru_load_rows(const Params& P, int l, int tile, int r0, int c0, u32x4 (&xr)[2][4]) {
;     const bf16* XR = (const bf16*)(P.ws + WS_XR);
;     const bool samp = tile * 64 >= NPT;
; #pragma unroll
;     for (int j = 0; j < 2; ++j) {
;         const int m = tile * 64 + r0 + 32 * j;
;         const int pos = samp ? ((m - NPT) & 3) : (m % LP);
; #pragma unroll
;         for (int i = 0; i < 4; ++i) {
;             u32x4 v = {0u, 0u, 0u, 0u};
;             if (pos - i >= 0) v = *(const u32x4*)(XR + (size_t)(m - i) * 1024 + c0);
;             else if (samp) { const float* buf = P.in[I_SC] + ((size_t)((l * 128 + ((m - NPT) >> 2)) * 3) + (3 + pos - i)) * 1024 + c0; v = pack8(*(const f32x4*)buf, *(const f32x4*)(buf + 4)); }
;             xr[j][i] = v;
;         }
;     }
.LBB0_1147:
	s_andn2_saveexec_b64 s[0:1], s[0:1]
	s_cbranch_execz .LBB0_1151
	s_and_b64 vcc, exec, s[56:57]
	s_cbranch_vccnz .LBB0_1150
	s_mov_b64 s[62:63], exec
	v_lshl_add_u64 v[6:7], v[2:3], 0, v[162:163]
	v_lshlrev_b64 v[6:7], 12, v[6:7]
	v_lshl_add_u64 v[10:11], v[166:167], 0, v[6:7]
	global_load_dwordx4 v[28:31], v[10:11], off
	global_load_dwordx4 v[82:85], v[10:11], off offset:16
	s_branch .LBB0_1151

; __device__ __forceinline__ u32x4 pack8(f32x4 a, f32x4 b) { u32x4 w; w.x = cvtpk(a[0], a[1]); w.y = cvtpk(a[2], a[3]); w.z = cvtpk(b[0], b[1]); w.w = cvtpk(b[2], b[3]); return w; }
; __device__ __forceinline__ void lru_load_rows(const Params& P, int l, int tile, int r0, int c0, u32x4 (&xr)[2][4]) {
;     const bf16* XR = (const bf16*)(P.ws + WS_XR);
;     const bool samp = tile * 64 >= NPT;
; #pragma unroll
;     for (int j = 0; j < 2; ++j) {
;         const int m = tile * 64 + r0 + 32 * j;
;         const int pos = samp ? ((m - NPT) & 3) : (m % LP);
; #pragma unroll
;         for (int i = 0; i < 4; ++i) {
;             u32x4 v = {0u, 0u, 0u, 0u};
;             if (pos - i >= 0) v = *(const u32x4*)(XR + (size_t)(m - i) * 1024 + c0);
;             else if (samp) { const float* buf = P.in[I_SC] + ((size_t)((l * 128 + ((m - NPT) >> 2)) * 3) + (3 + pos - i)) * 1024 + c0; v = pack8(*(const f32x4*)buf, *(const f32x4*)(buf + 4)); }
;             xr[j][i] = v;
;         }
;     }
.LBB0_1153:
	s_andn2_saveexec_b64 s[0:1], s[0:1]
	s_cbranch_execz .LBB0_1157
	s_and_b64 vcc, exec, s[56:57]
	s_cbranch_vccnz .LBB0_1156
	s_mov_b64 s[66:67], exec
	v_lshl_add_u64 v[0:1], v[2:3], 0, v[154:155]
	v_lshlrev_b64 v[0:1], 12, v[0:1]
	v_lshl_add_u64 v[4:5], v[166:167], 0, v[0:1]
	global_load_dwordx4 v[186:189], v[4:5], off
	global_load_dwordx4 v[226:229], v[4:5], off offset:16
	s_branch .LBB0_1157

; #define LAS __attribute__((address_space(3)))
; __device__ __forceinline__ float bf2f(unsigned b) { return __uint_as_float(b << 16); }
; __device__ __forceinline__ int crow(int reg, int h) { return (reg & 3) + 8 * (reg >> 2) + 4 * h; }
; #define MFMA32(a, b, c) __builtin_amdgcn_mfma_f32_32x32x16_bf16((a), (b), (c), 0, 0, 0)
; #define BAR_LDS() do { asm volatile("s_waitcnt lgkmcnt(0)" ::: "memory"); __builtin_amdgcn_s_barrier(); asm volatile("" ::: "memory"); } while (0)
; template <int MODE> __device__ __forceinline__ void lru_phase(const Params& P, LAS unsigned char* lds, int l, int tid_in) {
;     ...
;             for (int j = 0; j < 2; ++j) gw[j] = *(const u32x4*)(GG + (size_t)(t0 + r0 + 32 * j) * 1024 + c0);
;     ...
;         BAR_LDS();
;         if (cur) {
;             f32x16 ar, ai;
; #pragma unroll
;             for (int i = 0; i < 16; ++i) { ar[i] = 0.f; ai[i] = 0.f; }
; #pragma unroll
;             for (int kk = 0; kk < 8; ++kk) {
;                 const bf16x8 a = *(const LAS bf16x8*)(xcb + (rb * 32 + l32) * 136 + kk * 16 + h * 8);
;                 ar = MFMA32(a, br[kk], ar); ai = MFMA32(a, bi[kk], ai);
;             }
; #pragma unroll
;             for (int i = 0; i < 16; ++i) {
;                 const int r = rb * 32 + crow(i, h);
;                 const float rr = __builtin_amdgcn_rcpf(1.f + __builtin_amdgcn_exp2f(ar[i] * -L2E + nba)), ii = __builtin_amdgcn_rcpf(1.f + __builtin_amdgcn_exp2f(ai[i] * -L2E + nbx));
;                 const float a = __builtin_amdgcn_exp2f(ca * rr), mult = __builtin_amdgcn_sqrtf(fmaxf(1.f - a * a, 0.f));
;                 sa[r * 128 + cgate] = a; sb[r * 128 + cgate] = mult * ii * bf2f(xcb[r * 136 + cgate]);
;             }
.Lpf_samp_doneb:
.LBB0_1158:
	v_add_u32_e32 v0, s43, v177
	v_ashrrev_i32_e32 v1, 31, v0
	v_lshlrev_b64 v[0:1], 11, v[0:1]
	v_lshl_add_u64 v[0:1], v[164:165], 0, v[0:1]
	v_add_co_u32_e32 v2, vcc, 0x10000, v0
	s_nop 1
	v_addc_co_u32_e32 v3, vcc, 0, v1, vcc
	global_load_dwordx4 v[40:43], v[0:1], off
	global_load_dwordx4 v[44:47], v[2:3], off
.Lpf_moved_done:
	s_waitcnt lgkmcnt(0)
	s_barrier
	s_lshl_b32 s0, s41, 16
	s_add_i32 s1, s0, 0
	s_and_b64 vcc, exec, s[48:49]
	s_cbranch_vccnz .LBB0_1186
	ds_read_b128 v[0:3], v239
	ds_read_b128 v[82:85], v239 offset:32
	ds_read_b128 v[186:189], v239 offset:64
	ds_read_b128 v[226:229], v239 offset:96
	ds_read_b128 v[242:245], v239 offset:128
	ds_read_b128 v[246:249], v239 offset:160
	s_waitcnt lgkmcnt(5)
	v_mfma_f32_32x32x16_bf16 v[16:31], v[0:3], v[48:51], 0
	v_mfma_f32_32x32x16_bf16 v[0:15], v[0:3], v[56:59], 0
	s_waitcnt lgkmcnt(4)
	v_mfma_f32_32x32x16_bf16 v[16:31], v[82:85], v[52:55], v[16:31]
	v_mfma_f32_32x32x16_bf16 v[0:15], v[82:85], v[60:63], v[0:15]
	ds_read_b128 v[82:85], v239 offset:192
	s_waitcnt lgkmcnt(4)
	v_mfma_f32_32x32x16_bf16 v[16:31], v[186:189], v[64:67], v[16:31]
	v_mfma_f32_32x32x16_bf16 v[0:15], v[186:189], v[72:75], v[0:15]
	ds_read_b128 v[186:189], v239 offset:224
	s_waitcnt lgkmcnt(4)
	v_mfma_f32_32x32x16_bf16 v[16:31], v[226:229], v[68:71], v[16:31]
	v_mfma_f32_32x32x16_bf16 v[0:15], v[226:229], v[76:79], v[0:15]
	s_waitcnt lgkmcnt(3)
	v_mfma_f32_32x32x16_bf16 v[16:31], v[242:245], v[88:91], v[16:31]
	v_mfma_f32_32x32x16_bf16 v[0:15], v[242:245], v[96:99], v[0:15]
	s_waitcnt lgkmcnt(2)
	v_mfma_f32_32x32x16_bf16 v[16:31], v[246:249], v[92:95], v[16:31]
	v_mfma_f32_32x32x16_bf16 v[0:15], v[246:249], v[100:103], v[0:15]
	s_waitcnt lgkmcnt(1)
	v_mfma_f32_32x32x16_bf16 v[16:31], v[82:85], v[104:107], v[16:31]
	v_mfma_f32_32x32x16_bf16 v[0:15], v[82:85], v[112:115], v[0:15]
	s_waitcnt lgkmcnt(0)
	v_mfma_f32_32x32x16_bf16 v[16:31], v[186:189], v[108:111], v[16:31]
	v_mfma_f32_32x32x16_bf16 v[0:15], v[186:189], v[116:119], v[0:15]
	s_nop 10
	v_fmamk_f32 v16, v16, 0xbfb8aa3b, v178
	v_exp_f32_e32 v16, v16
	v_fmamk_f32 v17, v17, 0xbfb8aa3b, v178
	v_exp_f32_e32 v17, v17
	ds_read_u16 v82, v240
	v_add_f32_e32 v16, 1.0, v16
	v_rcp_f32_e32 v16, v16
	v_fmamk_f32 v0, v0, 0xbfb8aa3b, v179
	v_exp_f32_e32 v0, v0
	v_add_f32_e32 v17, 1.0, v17
	v_mul_f32_e32 v16, v180, v16
	v_exp_f32_e32 v16, v16
	v_rcp_f32_e32 v17, v17
	v_add_f32_e32 v0, 1.0, v0
	v_rcp_f32_e32 v0, v0
	v_fma_f32 v80, -v16, v16, 1.0
	v_max_f32_e32 v80, 0, v80
	v_sqrt_f32_e32 v80, v80
	v_fmamk_f32 v1, v1, 0xbfb8aa3b, v179
	v_mul_f32_e32 v17, v180, v17
	v_exp_f32_e32 v1, v1
	v_exp_f32_e32 v17, v17
	v_mul_f32_e32 v0, v0, v80
	s_waitcnt lgkmcnt(0)
	v_lshlrev_b32_e32 v80, 16, v82
	v_lshl_add_u32 v83, v193, 2, s1
	v_mul_f32_e32 v0, v0, v80
	ds_write2st64_b32 v83, v16, v0 offset0:68 offset1:196
	v_add_f32_e32 v0, 1.0, v1
	v_fma_f32 v1, -v17, v17, 1.0
	v_max_f32_e32 v1, 0, v1
	ds_read_u16 v16, v240 offset:272
	v_fmamk_f32 v18, v18, 0xbfb8aa3b, v178
	v_rcp_f32_e32 v0, v0
	v_sqrt_f32_e32 v1, v1
	v_exp_f32_e32 v18, v18
	v_add_u32_e32 v80, 0x80, v193
	v_lshl_add_u32 v80, v80, 2, s1
	v_mul_f32_e32 v0, v0, v1
	s_waitcnt lgkmcnt(0)
	v_lshlrev_b32_e32 v1, 16, v16
	v_add_f32_e32 v16, 1.0, v18
	v_rcp_f32_e32 v16, v16
	v_mul_f32_e32 v0, v0, v1
	v_fmamk_f32 v1, v2, 0xbfb8aa3b, v179
	v_exp_f32_e32 v1, v1
	v_mul_f32_e32 v2, v180, v16
	v_exp_f32_e32 v2, v2
	ds_write2st64_b32 v80, v17, v0 offset0:68 offset1:196
	v_add_f32_e32 v0, 1.0, v1
	ds_read_u16 v16, v240 offset:544
	v_fma_f32 v1, -v2, v2, 1.0
	v_max_f32_e32 v1, 0, v1
	v_fmamk_f32 v17, v19, 0xbfb8aa3b, v178
	v_rcp_f32_e32 v0, v0
	v_sqrt_f32_e32 v1, v1
	v_exp_f32_e32 v17, v17
	v_add_u32_e32 v18, 0x100, v193
	v_lshl_add_u32 v18, v18, 2, s1
	v_mul_f32_e32 v0, v0, v1
	s_waitcnt lgkmcnt(0)
	v_lshlrev_b32_e32 v1, 16, v16
	v_add_f32_e32 v16, 1.0, v17
	v_rcp_f32_e32 v16, v16
	v_mul_f32_e32 v0, v0, v1
	v_fmamk_f32 v1, v3, 0xbfb8aa3b, v179
	v_exp_f32_e32 v1, v1
	v_mul_f32_e32 v3, v180, v16
	v_exp_f32_e32 v3, v3
	ds_write2st64_b32 v18, v2, v0 offset0:68 offset1:196
	v_add_f32_e32 v0, 1.0, v1
	ds_read_u16 v2, v240 offset:816
	v_fma_f32 v1, -v3, v3, 1.0
	v_max_f32_e32 v1, 0, v1
	v_fmamk_f32 v16, v20, 0xbfb8aa3b, v178
	v_rcp_f32_e32 v0, v0
	v_sqrt_f32_e32 v1, v1
	v_exp_f32_e32 v16, v16
	v_add_u32_e32 v17, 0x180, v193
	v_lshl_add_u32 v17, v17, 2, s1
	v_mul_f32_e32 v0, v0, v1
	s_waitcnt lgkmcnt(0)
	v_lshlrev_b32_e32 v1, 16, v2
	v_add_f32_e32 v2, 1.0, v16
	v_rcp_f32_e32 v2, v2
	v_mul_f32_e32 v0, v0, v1
	v_fmamk_f32 v1, v4, 0xbfb8aa3b, v179
	v_exp_f32_e32 v1, v1
	v_mul_f32_e32 v2, v180, v2
	v_exp_f32_e32 v2, v2
	ds_write2st64_b32 v17, v3, v0 offset0:68 offset1:196
	v_add_f32_e32 v0, 1.0, v1
	ds_read_u16 v3, v240 offset:2176
	v_fma_f32 v1, -v2, v2, 1.0
	v_max_f32_e32 v1, 0, v1
	v_fmamk_f32 v4, v21, 0xbfb8aa3b, v178
	v_rcp_f32_e32 v0, v0
	v_sqrt_f32_e32 v1, v1
	v_exp_f32_e32 v4, v4
	v_lshl_add_u32 v16, v194, 2, s1
	v_mul_f32_e32 v0, v0, v1
	s_waitcnt lgkmcnt(0)
	v_lshlrev_b32_e32 v1, 16, v3
	v_add_f32_e32 v3, 1.0, v4
	v_rcp_f32_e32 v3, v3
	v_mul_f32_e32 v0, v0, v1
	v_fmamk_f32 v1, v5, 0xbfb8aa3b, v179
	v_exp_f32_e32 v1, v1
	v_mul_f32_e32 v3, v180, v3
	v_exp_f32_e32 v3, v3
	ds_write2st64_b32 v16, v2, v0 offset0:68 offset1:196
	v_add_f32_e32 v0, 1.0, v1
	ds_read_u16 v2, v240 offset:2448
	v_fma_f32 v1, -v3, v3, 1.0
	v_max_f32_e32 v1, 0, v1
	v_fmamk_f32 v4, v22, 0xbfb8aa3b, v178
	v_rcp_f32_e32 v0, v0
	v_sqrt_f32_e32 v1, v1
	v_exp_f32_e32 v4, v4
	v_lshl_add_u32 v5, v195, 2, s1
	v_mul_f32_e32 v0, v0, v1
	s_waitcnt lgkmcnt(0)
; __device__ __forceinline__ float bf2f(unsigned b) { return __uint_as_float(b << 16); }
; __device__ __forceinline__ int crow(int reg, int h) { return (reg & 3) + 8 * (reg >> 2) + 4 * h; }
; template <int MODE> __device__ __forceinline__ void lru_phase(const Params& P, LAS unsigned char* lds, int l, int tid_in) {
;     ...
; #pragma unroll
;             for (int i = 0; i < 16; ++i) {
;                 const int r = rb * 32 + crow(i, h);
;                 const float rr = __builtin_amdgcn_rcpf(1.f + __builtin_amdgcn_exp2f(ar[i] * -L2E + nba)), ii = __builtin_amdgcn_rcpf(1.f + __builtin_amdgcn_exp2f(ai[i] * -L2E + nbx));
;                 const float a = __builtin_amdgcn_exp2f(ca * rr), mult = __builtin_amdgcn_sqrtf(fmaxf(1.f - a * a, 0.f));
;                 sa[r * 128 + cgate] = a; sb[r * 128 + cgate] = mult * ii * bf2f(xcb[r * 136 + cgate]);
;             }
	v_lshlrev_b32_e32 v1, 16, v2
	v_add_f32_e32 v2, 1.0, v4
	v_rcp_f32_e32 v2, v2
	v_mul_f32_e32 v0, v0, v1
	v_fmamk_f32 v1, v6, 0xbfb8aa3b, v179
	v_exp_f32_e32 v1, v1
	v_mul_f32_e32 v2, v180, v2
	v_exp_f32_e32 v2, v2
	ds_write2st64_b32 v5, v3, v0 offset0:68 offset1:196
	v_add_f32_e32 v0, 1.0, v1
	ds_read_u16 v3, v240 offset:2720
	v_fma_f32 v1, -v2, v2, 1.0
	v_max_f32_e32 v1, 0, v1
	v_fmamk_f32 v4, v23, 0xbfb8aa3b, v178
	v_rcp_f32_e32 v0, v0
	v_sqrt_f32_e32 v1, v1
	v_exp_f32_e32 v4, v4
	v_lshl_add_u32 v5, v196, 2, s1
	v_fmamk_f32 v6, v31, 0xbfb8aa3b, v178
	v_mul_f32_e32 v0, v0, v1
	s_waitcnt lgkmcnt(0)
	v_lshlrev_b32_e32 v1, 16, v3
	v_add_f32_e32 v3, 1.0, v4
	v_rcp_f32_e32 v3, v3
	v_mul_f32_e32 v0, v0, v1
	v_fmamk_f32 v1, v7, 0xbfb8aa3b, v179
	v_exp_f32_e32 v1, v1
	v_mul_f32_e32 v3, v180, v3
	v_exp_f32_e32 v3, v3
	ds_write2st64_b32 v5, v2, v0 offset0:68 offset1:196
	v_add_f32_e32 v0, 1.0, v1
	ds_read_u16 v2, v240 offset:2992
	ds_read_u16 v7, v240 offset:7344
	v_fma_f32 v1, -v3, v3, 1.0
	v_max_f32_e32 v1, 0, v1
	v_fmamk_f32 v4, v24, 0xbfb8aa3b, v178
	v_rcp_f32_e32 v0, v0
	v_sqrt_f32_e32 v1, v1
	v_exp_f32_e32 v4, v4
	v_lshl_add_u32 v5, v197, 2, s1
	v_exp_f32_e32 v6, v6
	v_mul_f32_e32 v0, v0, v1
	s_waitcnt lgkmcnt(1)
	v_lshlrev_b32_e32 v1, 16, v2
	v_add_f32_e32 v2, 1.0, v4
	v_rcp_f32_e32 v2, v2
	v_mul_f32_e32 v0, v0, v1
	v_fmamk_f32 v1, v8, 0xbfb8aa3b, v179
	v_exp_f32_e32 v1, v1
	v_mul_f32_e32 v2, v180, v2
	v_exp_f32_e32 v2, v2
	ds_write2st64_b32 v5, v3, v0 offset0:68 offset1:196
	v_add_f32_e32 v0, 1.0, v1
	ds_read_u16 v3, v240 offset:4352
	v_fma_f32 v1, -v2, v2, 1.0
	v_max_f32_e32 v1, 0, v1
	v_fmamk_f32 v4, v25, 0xbfb8aa3b, v178
	v_rcp_f32_e32 v0, v0
	v_sqrt_f32_e32 v1, v1
	v_exp_f32_e32 v4, v4
	v_lshl_add_u32 v5, v198, 2, s1
	v_mul_f32_e32 v0, v0, v1
	s_waitcnt lgkmcnt(0)
	v_lshlrev_b32_e32 v1, 16, v3
	v_add_f32_e32 v3, 1.0, v4
	v_rcp_f32_e32 v3, v3
	v_mul_f32_e32 v0, v0, v1
	v_fmamk_f32 v1, v9, 0xbfb8aa3b, v179
	v_exp_f32_e32 v1, v1
	v_mul_f32_e32 v3, v180, v3
	v_exp_f32_e32 v3, v3
	ds_write2st64_b32 v5, v2, v0 offset0:68 offset1:196
	v_add_f32_e32 v0, 1.0, v1
	ds_read_u16 v2, v240 offset:4624
	v_fma_f32 v1, -v3, v3, 1.0
	v_max_f32_e32 v1, 0, v1
	v_fmamk_f32 v4, v26, 0xbfb8aa3b, v178
	v_rcp_f32_e32 v0, v0
	v_sqrt_f32_e32 v1, v1
	v_exp_f32_e32 v4, v4
	v_lshl_add_u32 v5, v199, 2, s1
	v_mul_f32_e32 v0, v0, v1
	s_waitcnt lgkmcnt(0)
	v_lshlrev_b32_e32 v1, 16, v2
	v_add_f32_e32 v2, 1.0, v4
	v_rcp_f32_e32 v2, v2
	v_mul_f32_e32 v0, v0, v1
	v_fmamk_f32 v1, v10, 0xbfb8aa3b, v179
	v_exp_f32_e32 v1, v1
	v_mul_f32_e32 v2, v180, v2
	v_exp_f32_e32 v2, v2
	ds_write2st64_b32 v5, v3, v0 offset0:68 offset1:196
	v_add_f32_e32 v0, 1.0, v1
	ds_read_u16 v3, v240 offset:4896
	v_fma_f32 v1, -v2, v2, 1.0
	v_max_f32_e32 v1, 0, v1
	v_fmamk_f32 v4, v27, 0xbfb8aa3b, v178
	v_rcp_f32_e32 v0, v0
	v_sqrt_f32_e32 v1, v1
	v_exp_f32_e32 v4, v4
	v_lshl_add_u32 v5, v200, 2, s1
	v_mul_f32_e32 v0, v0, v1
	s_waitcnt lgkmcnt(0)
	v_lshlrev_b32_e32 v1, 16, v3
	v_add_f32_e32 v3, 1.0, v4
	v_rcp_f32_e32 v3, v3
	v_mul_f32_e32 v0, v0, v1
	v_fmamk_f32 v1, v11, 0xbfb8aa3b, v179
	v_exp_f32_e32 v1, v1
	v_mul_f32_e32 v3, v180, v3
	v_exp_f32_e32 v3, v3
	ds_write2st64_b32 v5, v2, v0 offset0:68 offset1:196
	v_add_f32_e32 v0, 1.0, v1
	ds_read_u16 v2, v240 offset:5168
	v_fma_f32 v1, -v3, v3, 1.0
	v_max_f32_e32 v1, 0, v1
	v_fmamk_f32 v4, v28, 0xbfb8aa3b, v178
	v_rcp_f32_e32 v0, v0
	v_sqrt_f32_e32 v1, v1
	v_exp_f32_e32 v4, v4
	v_lshl_add_u32 v5, v201, 2, s1
	v_mul_f32_e32 v0, v0, v1
	s_waitcnt lgkmcnt(0)
	v_lshlrev_b32_e32 v1, 16, v2
	v_add_f32_e32 v2, 1.0, v4
	v_rcp_f32_e32 v2, v2
	v_mul_f32_e32 v0, v0, v1
	v_fmamk_f32 v1, v12, 0xbfb8aa3b, v179
	v_exp_f32_e32 v1, v1
	v_mul_f32_e32 v2, v180, v2
	v_exp_f32_e32 v2, v2
	ds_write2st64_b32 v5, v3, v0 offset0:68 offset1:196
	v_add_f32_e32 v0, 1.0, v1
	ds_read_u16 v3, v240 offset:6528
	v_fma_f32 v1, -v2, v2, 1.0
	v_max_f32_e32 v1, 0, v1
	v_fmamk_f32 v4, v29, 0xbfb8aa3b, v178
	v_rcp_f32_e32 v0, v0
	v_sqrt_f32_e32 v1, v1
	v_exp_f32_e32 v4, v4
	v_lshl_add_u32 v5, v202, 2, s1
	v_mul_f32_e32 v0, v0, v1
	s_waitcnt lgkmcnt(0)
	v_lshlrev_b32_e32 v1, 16, v3
	v_add_f32_e32 v3, 1.0, v4
	v_rcp_f32_e32 v3, v3
	v_mul_f32_e32 v0, v0, v1
	v_fmamk_f32 v1, v13, 0xbfb8aa3b, v179
	v_exp_f32_e32 v1, v1
	v_mul_f32_e32 v3, v180, v3
	v_exp_f32_e32 v3, v3
	ds_write2st64_b32 v5, v2, v0 offset0:68 offset1:196
	v_add_f32_e32 v0, 1.0, v1
	v_fmamk_f32 v2, v30, 0xbfb8aa3b, v178
	v_fma_f32 v1, -v3, v3, 1.0
	v_max_f32_e32 v1, 0, v1
	v_rcp_f32_e32 v0, v0
	v_sqrt_f32_e32 v1, v1
	v_exp_f32_e32 v2, v2
	ds_read_u16 v4, v240 offset:6800
	v_lshl_add_u32 v5, v203, 2, s1
	v_mul_f32_e32 v0, v0, v1
	v_add_f32_e32 v1, 1.0, v2
	v_rcp_f32_e32 v1, v1
	s_waitcnt lgkmcnt(0)
	v_lshlrev_b32_e32 v2, 16, v4
	v_fmamk_f32 v4, v14, 0xbfb8aa3b, v179
	v_exp_f32_e32 v4, v4
	v_mul_f32_e32 v1, v180, v1
	v_exp_f32_e32 v1, v1
	v_mul_f32_e32 v0, v0, v2
	ds_write2st64_b32 v5, v3, v0 offset0:68 offset1:196
	v_add_f32_e32 v3, 1.0, v6
	v_rcp_f32_e32 v3, v3
	v_add_f32_e32 v2, 1.0, v4
	v_fma_f32 v4, -v1, v1, 1.0
	v_max_f32_e32 v4, 0, v4
	v_rcp_f32_e32 v2, v2
	v_sqrt_f32_e32 v4, v4
	v_mul_f32_e32 v3, v180, v3
	v_fmamk_f32 v5, v15, 0xbfb8aa3b, v179
	v_exp_f32_e32 v3, v3
	v_exp_f32_e32 v5, v5
	v_mul_f32_e32 v2, v2, v4
	ds_read_u16 v4, v240 offset:7072
	v_fma_f32 v6, -v3, v3, 1.0
	v_add_f32_e32 v5, 1.0, v5
	v_max_f32_e32 v6, 0, v6
	v_rcp_f32_e32 v5, v5
	v_sqrt_f32_e32 v6, v6
	s_waitcnt lgkmcnt(0)
	v_lshlrev_b32_e32 v4, 16, v4
	v_lshl_add_u32 v0, v204, 2, s1
	v_mul_f32_e32 v2, v2, v4
	ds_write2st64_b32 v0, v1, v2 offset0:68 offset1:196
	v_mul_f32_e32 v1, v5, v6
	v_lshlrev_b32_e32 v2, 16, v7
	v_lshl_add_u32 v0, v205, 2, s1
	v_mul_f32_e32 v1, v1, v2
	ds_write2st64_b32 v0, v3, v1 offset0:68 offset1:196
